# FFN-up tile loops: prefetched tiles take a scalar-only head (tile-invariant per-lane offsets and the prefetch's scalar bases are kept alive across the epilogue), skipping ~150 VALU of address set-up p
# baseline (speedup 1.0000x reference)
.LBB0_941:
	s_cmp_lg_u32 s101, 0
	s_cbranch_scc1 .Lfh_942
	s_mul_hi_i32 s14, s39, 0x2aaaaaab
	s_lshr_b32 s15, s14, 31
	s_ashr_i32 s14, s14, 5
	s_add_i32 s15, s14, s15
	s_mul_i32 s14, s15, 0xc0
	s_sub_i32 s16, s39, s14
	s_sext_i32_i16 s14, s16
	s_bfe_u32 s14, s14, 0x4001b
	s_add_i32 s14, s16, s14
	s_sext_i32_i16 s17, s14
	s_and_b32 s14, s14, 0xfff0
	s_sub_i32 s14, s16, s14
	s_sext_i32_i16 s19, s14
	s_lshl_b32 s14, s17, 4
	s_and_b32 s14, s14, 0xffffff00
	v_mov_b32_e32 v148, v132
	v_mov_b32_e32 v18, v132
	s_add_i32 s17, s14, 0x500
	ds_read_b64 v[0:1], v133
	s_cmpk_lt_i32 s16, 0x60
	v_lshlrev_b32_e32 v9, 4, v18
	v_and_b32_e32 v8, 32, v18
	v_lshrrev_b32_e32 v10, 1, v18
	v_bitop3_b32 v8, v9, v8, 48 bitop3:0x6c
	s_cselect_b32 s18, s14, s17
	s_lshl_b32 s15, s15, 12
	s_lshl_b32 s16, s19, 8
	v_bfe_u32 v19, v18, 2, 4
	v_and_b32_e32 v20, 32, v10
	v_lshrrev_b32_e32 v21, 1, v8
	v_ashrrev_i32_e32 v22, 3, v18
	s_add_i32 s16, s16, s15
	v_or_b32_e32 v12, v21, v20
	v_and_or_b32 v8, v22, s20, v19
	s_ashr_i32 s17, s16, 31
	v_and_b32_e32 v11, 0xfffffc00, v9
	v_lshl_or_b32 v128, v8, 10, v12
	v_add_u32_e32 v8, 0x2000, v9
	v_add_u32_e32 v10, 0x4000, v9
	v_add_u32_e32 v9, 0x6000, v9
	s_lshl_b64 s[42:43], s[16:17], 11
	s_ashr_i32 s19, s18, 31
	v_ashrrev_i32_e32 v23, 7, v8
	v_ashrrev_i32_e32 v24, 7, v10
	v_ashrrev_i32_e32 v25, 7, v9
	s_waitcnt lgkmcnt(0)
	v_lshl_add_u64 v[2:3], v[0:1], 0, s[42:43]
	s_lshl_b64 s[18:19], s[18:19], 11
	v_and_or_b32 v8, v23, s20, v19
	v_and_or_b32 v10, v24, s20, v19
	v_and_or_b32 v9, v25, s20, v19
	v_add_u32_e32 v149, 0, v11
	v_lshl_add_u64 v[4:5], v[2:3], 0, s[4:5]
	v_lshl_add_u64 v[0:1], v[0:1], 0, s[18:19]
	v_lshl_or_b32 v8, v8, 10, v12
	v_lshl_or_b32 v10, v10, 10, v12
	v_lshl_or_b32 v12, v9, 10, v12
	v_add_u32_e32 v9, 0x8000, v149
	v_lshlrev_b64 v[14:15], 1, v[128:129]
	v_readfirstlane_b32 s15, v149
	v_lshl_add_u64 v[6:7], v[0:1], 0, s[6:7]
	v_add_co_u32_e32 v16, vcc, v4, v14
	v_addc_co_u32_e32 v17, vcc, v5, v15, vcc
	s_mov_b32 m0, s15
	v_readfirstlane_b32 s15, v9
	v_mov_b32_e32 v9, v129
	v_add_u32_e32 v11, 0x2000, v149
	s_cmp_lg_u32 s101, 0
	s_cbranch_scc1 .Lnxh_942_7
	global_load_lds_dwordx4 v[16:17], off

.Lnxj_942_11:
	s_mov_b32 m0, s100
	s_nop 0
	global_load_lds_dwordx4 v146, s[98:99]
	s_add_i32 m0, s100, 0x8000
	s_nop 0
	global_load_lds_dwordx4 v138, vcc
	s_add_i32 m0, s100, 0x2000
	s_nop 0
	global_load_lds_dwordx4 v144, s[98:99]
	s_add_i32 m0, s100, 0xa000
	s_nop 0
	global_load_lds_dwordx4 v136, vcc
	s_add_i32 m0, s100, 0x4000
	s_nop 0
	global_load_lds_dwordx4 v142, s[98:99]
	s_add_i32 m0, s100, 0xc000
	s_nop 0
	global_load_lds_dwordx4 v134, vcc
	s_add_i32 m0, s100, 0x6000
	s_nop 0
	global_load_lds_dwordx4 v140, s[98:99]
	s_add_i32 m0, s100, 0xe000
	s_nop 0
	global_load_lds_dwordx4 v130, vcc
	v_writelane_b32 v239, vcc_lo, 0
	v_writelane_b32 v239, vcc_hi, 1
	s_mov_b32 s101, 1
.Lnxn_942:
	s_waitcnt lgkmcnt(0)
	s_waitcnt lgkmcnt(3)
	v_mfma_f32_16x16x32_bf16 v[108:111], v[178:181], v[162:165], v[108:111]
	v_mfma_f32_16x16x32_bf16 v[92:95], v[178:181], v[166:169], v[92:95]
	v_mfma_f32_16x16x32_bf16 v[76:79], v[178:181], v[170:173], v[76:79]
	v_mfma_f32_16x16x32_bf16 v[60:63], v[178:181], v[174:177], v[60:63]
	ds_read_b128 v[240:243], v197
	ds_read_b128 v[244:247], v198
	s_waitcnt lgkmcnt(4)
	v_mfma_f32_16x16x32_bf16 v[104:107], v[182:185], v[162:165], v[104:107]
	v_mfma_f32_16x16x32_bf16 v[88:91], v[182:185], v[166:169], v[88:91]
	v_mfma_f32_16x16x32_bf16 v[72:75], v[182:185], v[170:173], v[72:75]
	v_mfma_f32_16x16x32_bf16 v[56:59], v[182:185], v[174:177], v[56:59]
	ds_read_b128 v[248:251], v199
	ds_read_b128 v[252:255], v200
	s_waitcnt lgkmcnt(5)
	v_mfma_f32_16x16x32_bf16 v[100:103], v[186:189], v[162:165], v[100:103]
	v_mfma_f32_16x16x32_bf16 v[84:87], v[186:189], v[166:169], v[84:87]
	v_mfma_f32_16x16x32_bf16 v[68:71], v[186:189], v[170:173], v[68:71]
	v_mfma_f32_16x16x32_bf16 v[52:55], v[186:189], v[174:177], v[52:55]
	s_waitcnt lgkmcnt(4)
	v_mfma_f32_16x16x32_bf16 v[96:99], v[190:193], v[162:165], v[96:99]
	v_mfma_f32_16x16x32_bf16 v[80:83], v[190:193], v[166:169], v[80:83]
	v_mfma_f32_16x16x32_bf16 v[64:67], v[190:193], v[170:173], v[64:67]
	v_mfma_f32_16x16x32_bf16 v[48:51], v[190:193], v[174:177], v[48:51]
	ds_read_b128 v[162:165], v161 offset:1024
	ds_read_b128 v[166:169], v194 offset:1024
	ds_read_b128 v[170:173], v195 offset:1024
	ds_read_b128 v[174:177], v196 offset:1024
	s_waitcnt lgkmcnt(4)
	v_mfma_f32_16x16x32_bf16 v[44:47], v[178:181], v[240:243], v[44:47]
	v_mfma_f32_16x16x32_bf16 v[28:31], v[178:181], v[244:247], v[28:31]
	v_mfma_f32_16x16x32_bf16 v[12:15], v[178:181], v[248:251], v[12:15]
	v_mfma_f32_16x16x32_bf16 v[112:115], v[178:181], v[252:255], v[112:115]
	ds_read_b128 v[178:181], v128 offset:33792
	v_mfma_f32_16x16x32_bf16 v[40:43], v[182:185], v[240:243], v[40:43]
	v_mfma_f32_16x16x32_bf16 v[24:27], v[182:185], v[244:247], v[24:27]
	v_mfma_f32_16x16x32_bf16 v[8:11], v[182:185], v[248:251], v[8:11]
	v_mfma_f32_16x16x32_bf16 v[116:119], v[182:185], v[252:255], v[116:119]
	ds_read_b128 v[182:185], v128 offset:35840
	v_mfma_f32_16x16x32_bf16 v[36:39], v[186:189], v[240:243], v[36:39]
	v_mfma_f32_16x16x32_bf16 v[20:23], v[186:189], v[244:247], v[20:23]
	v_mfma_f32_16x16x32_bf16 v[4:7], v[186:189], v[248:251], v[4:7]
	v_mfma_f32_16x16x32_bf16 v[120:123], v[186:189], v[252:255], v[120:123]
	ds_read_b128 v[186:189], v128 offset:37888
	v_mfma_f32_16x16x32_bf16 v[32:35], v[190:193], v[240:243], v[32:35]
	v_mfma_f32_16x16x32_bf16 v[16:19], v[190:193], v[244:247], v[16:19]
	v_mfma_f32_16x16x32_bf16 v[0:3], v[190:193], v[248:251], v[0:3]
	v_mfma_f32_16x16x32_bf16 v[124:127], v[190:193], v[252:255], v[124:127]
	ds_read_b128 v[190:193], v128 offset:39936
	s_waitcnt lgkmcnt(3)
	v_mfma_f32_16x16x32_bf16 v[108:111], v[178:181], v[162:165], v[108:111]
	v_mfma_f32_16x16x32_bf16 v[92:95], v[178:181], v[166:169], v[92:95]
	v_mfma_f32_16x16x32_bf16 v[76:79], v[178:181], v[170:173], v[76:79]
	v_mfma_f32_16x16x32_bf16 v[60:63], v[178:181], v[174:177], v[60:63]
	ds_read_b128 v[240:243], v197 offset:1024
	ds_read_b128 v[244:247], v198 offset:1024
	s_waitcnt lgkmcnt(4)
	v_mfma_f32_16x16x32_bf16 v[104:107], v[182:185], v[162:165], v[104:107]
	v_mfma_f32_16x16x32_bf16 v[88:91], v[182:185], v[166:169], v[88:91]
	v_mfma_f32_16x16x32_bf16 v[72:75], v[182:185], v[170:173], v[72:75]
	v_mfma_f32_16x16x32_bf16 v[56:59], v[182:185], v[174:177], v[56:59]
	ds_read_b128 v[248:251], v199 offset:1024
	ds_read_b128 v[252:255], v200 offset:1024
	s_waitcnt lgkmcnt(5)
	v_mfma_f32_16x16x32_bf16 v[100:103], v[186:189], v[162:165], v[100:103]
	v_mfma_f32_16x16x32_bf16 v[84:87], v[186:189], v[166:169], v[84:87]
	v_mfma_f32_16x16x32_bf16 v[68:71], v[186:189], v[170:173], v[68:71]
	v_mfma_f32_16x16x32_bf16 v[52:55], v[186:189], v[174:177], v[52:55]
	s_waitcnt lgkmcnt(4)
	v_mfma_f32_16x16x32_bf16 v[96:99], v[190:193], v[162:165], v[96:99]
	v_mfma_f32_16x16x32_bf16 v[80:83], v[190:193], v[166:169], v[80:83]
	v_mfma_f32_16x16x32_bf16 v[64:67], v[190:193], v[170:173], v[64:67]
	v_mfma_f32_16x16x32_bf16 v[48:51], v[190:193], v[174:177], v[48:51]
	s_waitcnt lgkmcnt(0)
	v_mfma_f32_16x16x32_bf16 v[44:47], v[178:181], v[240:243], v[44:47]
	v_mfma_f32_16x16x32_bf16 v[28:31], v[178:181], v[244:247], v[28:31]
	v_mfma_f32_16x16x32_bf16 v[12:15], v[178:181], v[248:251], v[12:15]
	v_mfma_f32_16x16x32_bf16 v[112:115], v[178:181], v[252:255], v[112:115]
	v_mfma_f32_16x16x32_bf16 v[40:43], v[182:185], v[240:243], v[40:43]
	v_mfma_f32_16x16x32_bf16 v[24:27], v[182:185], v[244:247], v[24:27]
	v_mfma_f32_16x16x32_bf16 v[8:11], v[182:185], v[248:251], v[8:11]
	v_mfma_f32_16x16x32_bf16 v[116:119], v[182:185], v[252:255], v[116:119]
	v_mfma_f32_16x16x32_bf16 v[36:39], v[186:189], v[240:243], v[36:39]
	v_mfma_f32_16x16x32_bf16 v[20:23], v[186:189], v[244:247], v[20:23]
	v_mfma_f32_16x16x32_bf16 v[4:7], v[186:189], v[248:251], v[4:7]
	v_mfma_f32_16x16x32_bf16 v[120:123], v[186:189], v[252:255], v[120:123]
	v_mfma_f32_16x16x32_bf16 v[32:35], v[190:193], v[240:243], v[32:35]
	v_mfma_f32_16x16x32_bf16 v[16:19], v[190:193], v[244:247], v[16:19]
	v_mfma_f32_16x16x32_bf16 v[0:3], v[190:193], v[248:251], v[0:3]
	v_mfma_f32_16x16x32_bf16 v[124:127], v[190:193], v[252:255], v[124:127]
	v_mov_b32_e32 v128, s3
	s_waitcnt vmcnt(8)
	s_barrier
	ds_read_b64 v[240:241], v128
	v_ashrrev_i32_e32 v128, 1, v148
	v_and_b32_e32 v128, 0xffffff80, v128
	v_add_u32_e32 v128, s16, v128
	s_ashr_i32 s15, s14, 31
	s_waitcnt lgkmcnt(0)
	v_mad_i64_i32 v[240:241], s[16:17], v128, s23, v[240:241]
	v_and_b32_e32 v128, 0xc0, v148
	v_lshrrev_b32_e32 v243, 6, v148
	v_lshl_add_u64 v[240:241], s[14:15], 1, v[240:241]
	v_lshlrev_b32_e32 v128, 1, v128
	v_add_co_u32_e32 v240, vcc, v240, v128
	v_addc_co_u32_e32 v241, vcc, v241, v129, vcc
	v_mul_lo_u32 v128, v243, s27
	v_add_u32_e32 v243, s24, v128
	v_lshrrev_b32_e32 v128, 1, v148
	v_and_b32_e32 v244, 24, v128
	v_lshlrev_b32_e32 v128, 4, v148
	v_bfe_u32 v245, v148, 3, 3
	v_and_b32_e32 v242, 15, v148
	v_and_b32_e32 v128, 0x70, v128
	v_mul_u32_u24_e32 v246, 0x90, v245
	v_add_co_u32_e32 v240, vcc, v240, v128
	v_addc_co_u32_e32 v241, vcc, v241, v129, vcc
	v_add3_u32 v246, v243, v128, v246
	v_mul_u32_u24_e32 v128, 0x90, v242
	v_add3_u32 v242, v243, v244, v128
	v_cvt_pk_bf16_f32 v108, v108, v109
	v_cvt_pk_bf16_f32 v109, v110, v111
	v_cvt_pk_bf16_f32 v104, v104, v105
	v_cvt_pk_bf16_f32 v105, v106, v107
	v_cvt_pk_bf16_f32 v100, v100, v101
	v_cvt_pk_bf16_f32 v101, v102, v103
	v_cvt_pk_bf16_f32 v96, v96, v97
	v_cvt_pk_bf16_f32 v97, v98, v99
	v_cvt_pk_bf16_f32 v92, v92, v93
	v_cvt_pk_bf16_f32 v93, v94, v95
	v_cvt_pk_bf16_f32 v88, v88, v89
	v_cvt_pk_bf16_f32 v89, v90, v91
	v_cvt_pk_bf16_f32 v84, v84, v85
	v_cvt_pk_bf16_f32 v85, v86, v87
	v_cvt_pk_bf16_f32 v80, v80, v81
	v_cvt_pk_bf16_f32 v81, v82, v83
	v_cvt_pk_bf16_f32 v76, v76, v77
	v_cvt_pk_bf16_f32 v77, v78, v79
	v_cvt_pk_bf16_f32 v72, v72, v73
	v_cvt_pk_bf16_f32 v73, v74, v75
	v_cvt_pk_bf16_f32 v68, v68, v69
	v_cvt_pk_bf16_f32 v69, v70, v71
	v_cvt_pk_bf16_f32 v64, v64, v65
	v_cvt_pk_bf16_f32 v65, v66, v67
	v_cvt_pk_bf16_f32 v60, v60, v61
	v_cvt_pk_bf16_f32 v61, v62, v63
	v_cvt_pk_bf16_f32 v56, v56, v57
	v_cvt_pk_bf16_f32 v57, v58, v59
	v_cvt_pk_bf16_f32 v52, v52, v53
	v_cvt_pk_bf16_f32 v53, v54, v55
	v_cvt_pk_bf16_f32 v48, v48, v49
	v_cvt_pk_bf16_f32 v49, v50, v51
	ds_write_b64 v242, v[108:109]
	ds_write_b64 v242, v[104:105] offset:32
	ds_write_b64 v242, v[100:101] offset:64
	ds_write_b64 v242, v[96:97] offset:96
	ds_write_b64 v242, v[92:93] offset:2304
	ds_write_b64 v242, v[88:89] offset:2336
	ds_write_b64 v242, v[84:85] offset:2368
	ds_write_b64 v242, v[80:81] offset:2400
	ds_write_b64 v242, v[76:77] offset:4608
	ds_write_b64 v242, v[72:73] offset:4640
	ds_write_b64 v242, v[68:69] offset:4672
	ds_write_b64 v242, v[64:65] offset:4704
	ds_write_b64 v242, v[60:61] offset:6912
	ds_write_b64 v242, v[56:57] offset:6944
	ds_write_b64 v242, v[52:53] offset:6976
	ds_write_b64 v242, v[48:49] offset:7008
	ds_read_b128 v[48:51], v246
	v_mul_u32_u24_e32 v54, 0xc00, v245
	v_lshl_add_u64 v[52:53], v[240:241], 0, s[12:13]
	v_lshlrev_b32_e32 v128, 1, v54
	v_add_co_u32_e32 v54, vcc, v52, v128
	v_addc_co_u32_e32 v55, vcc, v53, v129, vcc
	s_waitcnt lgkmcnt(0)
	global_store_dwordx4 v[54:55], v[48:51], off nt
	ds_read_b128 v[48:51], v246 offset:1152
	v_add_co_u32_e32 v56, vcc, s21, v54
	v_cvt_pk_bf16_f32 v0, v0, v1
	s_nop 0
	v_addc_co_u32_e32 v57, vcc, 0, v55, vcc
	s_waitcnt lgkmcnt(0)
	global_store_dwordx4 v[56:57], v[48:51], off nt
	ds_read_b128 v[48:51], v246 offset:2304
	v_add_co_u32_e32 v56, vcc, s25, v54
	v_cvt_pk_bf16_f32 v1, v2, v3
	s_nop 0
	v_addc_co_u32_e32 v57, vcc, 0, v55, vcc
	s_waitcnt lgkmcnt(0)
	global_store_dwordx4 v[56:57], v[48:51], off nt
	ds_read_b128 v[48:51], v246 offset:3456
	v_add_co_u32_e32 v56, vcc, s28, v54
	v_cvt_pk_bf16_f32 v44, v44, v45
	s_nop 0
	v_addc_co_u32_e32 v57, vcc, 0, v55, vcc
	s_waitcnt lgkmcnt(0)
	global_store_dwordx4 v[56:57], v[48:51], off nt
	ds_read_b128 v[48:51], v246 offset:4608
	v_or_b32_e32 v56, 0x30000, v128
	v_mov_b32_e32 v57, v129
	v_add_co_u32_e32 v56, vcc, v52, v56
	v_addc_co_u32_e32 v57, vcc, v53, v57, vcc
	v_cvt_pk_bf16_f32 v45, v46, v47
	s_waitcnt lgkmcnt(0)
	global_store_dwordx4 v[56:57], v[48:51], off nt
	ds_read_b128 v[48:51], v246 offset:5760
	v_add_u32_e32 v56, 0x3c000, v128
	v_mov_b32_e32 v57, v129
	v_add_co_u32_e32 v56, vcc, v52, v56
	v_addc_co_u32_e32 v57, vcc, v53, v57, vcc
	v_cvt_pk_bf16_f32 v40, v40, v41
	s_waitcnt lgkmcnt(0)
	global_store_dwordx4 v[56:57], v[48:51], off nt
	ds_read_b128 v[48:51], v246 offset:6912
	v_add_u32_e32 v56, 0x48000, v128
	v_mov_b32_e32 v57, v129
	v_add_co_u32_e32 v56, vcc, v52, v56
	v_addc_co_u32_e32 v57, vcc, v53, v57, vcc
	v_add_u32_e32 v128, 0x54000, v128
	s_waitcnt lgkmcnt(0)
	global_store_dwordx4 v[56:57], v[48:51], off nt
	ds_read_b128 v[48:51], v246 offset:8064
	v_add_co_u32_e32 v52, vcc, v52, v128
	v_addc_co_u32_e32 v53, vcc, v53, v129, vcc
	v_cvt_pk_bf16_f32 v41, v42, v43
	v_cvt_pk_bf16_f32 v36, v36, v37
	v_cvt_pk_bf16_f32 v37, v38, v39
	s_waitcnt lgkmcnt(0)
	global_store_dwordx4 v[52:53], v[48:51], off nt
	ds_write_b64 v242, v[0:1] offset:4704
	v_cvt_pk_bf16_f32 v0, v112, v113
	v_cvt_pk_bf16_f32 v1, v114, v115
	ds_write_b64 v242, v[0:1] offset:6912
	v_cvt_pk_bf16_f32 v0, v116, v117
	v_cvt_pk_bf16_f32 v1, v118, v119
	ds_write_b64 v242, v[0:1] offset:6944
	v_cvt_pk_bf16_f32 v0, v120, v121
	v_cvt_pk_bf16_f32 v1, v122, v123
	v_cvt_pk_bf16_f32 v32, v32, v33
	v_cvt_pk_bf16_f32 v33, v34, v35
	v_cvt_pk_bf16_f32 v28, v28, v29
	v_cvt_pk_bf16_f32 v29, v30, v31
	v_cvt_pk_bf16_f32 v24, v24, v25
	v_cvt_pk_bf16_f32 v25, v26, v27
	v_cvt_pk_bf16_f32 v20, v20, v21
	v_cvt_pk_bf16_f32 v21, v22, v23
	v_cvt_pk_bf16_f32 v16, v16, v17
	v_cvt_pk_bf16_f32 v17, v18, v19
	v_cvt_pk_bf16_f32 v12, v12, v13
	v_cvt_pk_bf16_f32 v13, v14, v15
	v_cvt_pk_bf16_f32 v8, v8, v9
	v_cvt_pk_bf16_f32 v9, v10, v11
	v_cvt_pk_bf16_f32 v4, v4, v5
	v_cvt_pk_bf16_f32 v5, v6, v7
	ds_write_b64 v242, v[0:1] offset:6976
	v_cvt_pk_bf16_f32 v0, v124, v125
	v_cvt_pk_bf16_f32 v1, v126, v127
	ds_write_b64 v242, v[44:45]
	ds_write_b64 v242, v[40:41] offset:32
	ds_write_b64 v242, v[36:37] offset:64
	ds_write_b64 v242, v[32:33] offset:96
	ds_write_b64 v242, v[28:29] offset:2304
	ds_write_b64 v242, v[24:25] offset:2336
	ds_write_b64 v242, v[20:21] offset:2368
	ds_write_b64 v242, v[16:17] offset:2400
	ds_write_b64 v242, v[12:13] offset:4608
	ds_write_b64 v242, v[8:9] offset:4640
	ds_write_b64 v242, v[4:5] offset:4672
	ds_write_b64 v242, v[0:1] offset:7008
	ds_read_b128 v[0:3], v246
	v_add_co_u32_e32 v4, vcc, s29, v54
	s_add_i32 s39, s39, s40
	s_nop 0
	v_addc_co_u32_e32 v5, vcc, 0, v55, vcc
	s_waitcnt lgkmcnt(0)
	global_store_dwordx4 v[4:5], v[0:3], off nt
	ds_read_b128 v[0:3], v246 offset:1152
	v_add_co_u32_e32 v4, vcc, s30, v54
	s_cmpk_gt_i32 s39, 0x5ff
	s_nop 0
	v_addc_co_u32_e32 v5, vcc, 0, v55, vcc
	s_waitcnt lgkmcnt(0)
	global_store_dwordx4 v[4:5], v[0:3], off nt
	ds_read_b128 v[0:3], v246 offset:2304
	v_add_co_u32_e32 v4, vcc, s31, v54
	s_nop 1
	v_addc_co_u32_e32 v5, vcc, 0, v55, vcc
	s_waitcnt lgkmcnt(0)
	global_store_dwordx4 v[4:5], v[0:3], off nt
	ds_read_b128 v[0:3], v246 offset:3456
	v_add_co_u32_e32 v4, vcc, s34, v54
	s_nop 1
	v_addc_co_u32_e32 v5, vcc, 0, v55, vcc
	s_waitcnt lgkmcnt(0)
	global_store_dwordx4 v[4:5], v[0:3], off nt
	ds_read_b128 v[0:3], v246 offset:4608
	v_add_co_u32_e32 v4, vcc, s35, v54
	s_nop 1
	v_addc_co_u32_e32 v5, vcc, 0, v55, vcc
	s_waitcnt lgkmcnt(0)
	global_store_dwordx4 v[4:5], v[0:3], off nt
	ds_read_b128 v[0:3], v246 offset:5760
	v_add_co_u32_e32 v4, vcc, s38, v54
	s_nop 1
	v_addc_co_u32_e32 v5, vcc, 0, v55, vcc
	s_waitcnt lgkmcnt(0)
	global_store_dwordx4 v[4:5], v[0:3], off nt
	ds_read_b128 v[0:3], v246 offset:6912
	v_add_co_u32_e32 v4, vcc, 0xa8000, v54
	s_nop 1
	v_addc_co_u32_e32 v5, vcc, 0, v55, vcc
	s_waitcnt lgkmcnt(0)
	global_store_dwordx4 v[4:5], v[0:3], off nt
	ds_read_b128 v[0:3], v246 offset:8064
	v_add_co_u32_e32 v4, vcc, 0xb4000, v54
	s_nop 1
	v_addc_co_u32_e32 v5, vcc, 0, v55, vcc
	s_waitcnt lgkmcnt(0)
	global_store_dwordx4 v[4:5], v[0:3], off nt
	s_cbranch_scc0 .LBB0_941
	s_branch .Lfh_end_942
.Lfh_942:
	s_mul_hi_i32 s14, s39, 0x2aaaaaab
	s_lshr_b32 s15, s14, 31
	s_ashr_i32 s14, s14, 5
	s_add_i32 s15, s14, s15
	s_mul_i32 s14, s15, 0xc0
	s_sub_i32 s16, s39, s14
	s_sext_i32_i16 s14, s16
	s_bfe_u32 s14, s14, 0x4001b
	s_add_i32 s14, s16, s14
	s_sext_i32_i16 s17, s14
	s_and_b32 s14, s14, 0xfff0
	s_sub_i32 s14, s16, s14
	s_sext_i32_i16 s19, s14
	s_lshl_b32 s14, s17, 4
	s_and_b32 s14, s14, 0xffffff00
	s_add_i32 s17, s14, 0x500
	s_cmpk_lt_i32 s16, 0x60
	s_cselect_b32 s18, s14, s17
	s_lshl_b32 s15, s15, 12
	s_lshl_b32 s16, s19, 8
	s_add_i32 s16, s16, s15
	s_ashr_i32 s17, s16, 31
	s_lshl_b64 s[42:43], s[16:17], 11
	s_ashr_i32 s19, s18, 31
	s_lshl_b64 s[18:19], s[18:19], 11
	s_mov_b64 s[18:19], 0
	s_mov_b32 s15, 0
	v_mov_b32_e32 v148, v132
	s_waitcnt vmcnt(16) lgkmcnt(0)
	s_barrier
	v_readfirstlane_b32 s100, v149
	s_and_b32 s17, s15, 0x10000
	s_xor_b32 s42, s17, 0x10000
	s_add_i32 s17, s17, 0
	v_add3_u32 v128, s17, v150, v151
	v_add3_u32 v161, s17, v150, v152
	v_add3_u32 v194, s17, v154, v153
	v_add3_u32 v195, s17, v154, v155
	v_add3_u32 v196, s17, v154, v156
	v_add3_u32 v197, s17, v154, v157
	v_add3_u32 v198, s17, v154, v158
	v_add3_u32 v199, s17, v154, v159
	v_add3_u32 v200, s17, v154, v160
	ds_read_b128 v[178:181], v128 offset:32768
	ds_read_b128 v[162:165], v161
	ds_read_b128 v[166:169], v194
	ds_read_b128 v[170:173], v195
	ds_read_b128 v[174:177], v196
	ds_read_b128 v[182:185], v128 offset:34816
	ds_read_b128 v[186:189], v128 offset:36864
	ds_read_b128 v[190:193], v128 offset:38912
	s_add_i32 s101, s100, s42
	v_readlane_b32 vcc_lo, v239, 0
	v_readlane_b32 vcc_hi, v239, 1
	s_add_u32 s98, s98, 0x80
	s_addc_u32 s99, s99, 0
	s_add_u32 vcc_lo, vcc_lo, 0x80
	s_addc_u32 vcc_hi, vcc_hi, 0
	s_mov_b32 m0, s101
	s_nop 0
	global_load_lds_dwordx4 v146, s[98:99]
	s_add_i32 m0, s101, 0x8000
	s_nop 0
	global_load_lds_dwordx4 v138, vcc
	s_add_i32 m0, s101, 0x2000
	s_nop 0
	global_load_lds_dwordx4 v144, s[98:99]
	s_add_i32 m0, s101, 0xa000
	s_nop 0
	global_load_lds_dwordx4 v136, vcc
	s_add_i32 m0, s101, 0x4000
	s_nop 0
	global_load_lds_dwordx4 v142, s[98:99]
	s_add_i32 m0, s101, 0xc000
	s_nop 0
	global_load_lds_dwordx4 v134, vcc
	s_add_i32 m0, s101, 0x6000
	s_nop 0
	global_load_lds_dwordx4 v140, s[98:99]
	s_add_i32 m0, s101, 0xe000
	s_nop 0
	global_load_lds_dwordx4 v130, vcc
	s_branch .LBB0_942
.Lfh_end_942:
.LBB0_944:
	s_add_i32 s3, 0, 0x240a8
	v_mov_b32_e32 v0, s3
	s_add_i32 s3, 0, 0x240c8
	v_mov_b32_e32 v2, s3
	ds_read_b64 v[0:1], v0
	ds_read_b32 v2, v2
	s_waitcnt vmcnt(0)
	s_waitcnt lgkmcnt(0)
	s_barrier
	v_readfirstlane_b32 s3, v2
	s_and_saveexec_b64 s[38:39], s[46:47]
	s_cbranch_execz .LBB0_988
	s_add_i32 s4, 0, 0x240c0
	v_mov_b32_e32 v2, s4
	s_waitcnt vmcnt(0) expcnt(0) lgkmcnt(0)
	ds_read_b32 v4, v2
	s_add_i32 s4, 0, 0x240c4
	v_mov_b32_e32 v2, s4
	ds_read_b32 v6, v2
	s_waitcnt lgkmcnt(1)
	v_cmp_ne_u32_e32 vcc, 0, v4
	s_cbranch_vccnz .LBB0_959
	v_readlane_b32 s4, v238, 0
	s_mul_i32 s22, s41, s4
	s_mov_b64 s[4:5], 0x1d400200
	v_lshl_add_u64 v[2:3], v[0:1], 0, s[4:5]
	s_mov_b64 s[4:5], 0x1d400400
	v_lshl_add_u64 v[4:5], v[0:1], 0, s[4:5]
	s_mov_b64 s[4:5], 0x1d400500
	s_waitcnt lgkmcnt(0)
	v_lshl_add_u64 v[6:7], v[0:1], 0, s[4:5]
	s_mov_b64 s[4:5], 0x1d400600
	v_lshl_add_u64 v[8:9], v[0:1], 0, s[4:5]
	s_mov_b64 s[4:5], 0x1d400700
	v_lshl_add_u64 v[10:11], v[0:1], 0, s[4:5]
	s_mov_b64 s[4:5], 0x1d400800
	v_lshl_add_u64 v[12:13], v[0:1], 0, s[4:5]
	s_mov_b64 s[4:5], 0x1d400900
	v_lshl_add_u64 v[14:15], v[0:1], 0, s[4:5]
	s_mov_b64 s[4:5], 0x1d400a00
	v_lshl_add_u64 v[16:17], v[0:1], 0, s[4:5]
	s_mov_b64 s[4:5], 0x1d400b00
	v_lshl_add_u64 v[18:19], v[0:1], 0, s[4:5]
	s_mov_b64 s[4:5], 0x1d400c00
	v_lshl_add_u64 v[20:21], v[0:1], 0, s[4:5]
	s_mov_b64 s[4:5], 0x1d400d00
	v_lshl_add_u64 v[22:23], v[0:1], 0, s[4:5]
	s_mov_b64 s[4:5], 0x1d400e00
	v_lshl_add_u64 v[24:25], v[0:1], 0, s[4:5]
	s_mov_b64 s[4:5], 0x1d400f00
	v_lshl_add_u64 v[26:27], v[0:1], 0, s[4:5]
	s_mov_b64 s[4:5], 0x1d401000
	v_lshl_add_u64 v[28:29], v[0:1], 0, s[4:5]
	s_mov_b64 s[4:5], 0x1d401100
	v_lshl_add_u64 v[30:31], v[0:1], 0, s[4:5]
	s_mov_b64 s[4:5], 0x1d401200
	v_lshl_add_u64 v[32:33], v[0:1], 0, s[4:5]
	s_mov_b64 s[4:5], 0x1d401300
	s_mul_i32 s22, s22, s40
	v_lshl_add_u64 v[34:35], v[0:1], 0, s[4:5]
	s_mov_b32 s23, 1
	s_mov_b64 s[4:5], 0
	s_branch .LBB0_949

.LBB0_1039:
	s_cmp_lg_u32 s101, 0
	s_cbranch_scc1 .Lfh_1040
	s_mul_hi_i32 s14, s42, 0x66666667
	s_lshr_b32 s15, s14, 31
	s_ashr_i32 s14, s14, 6
	s_add_i32 s15, s14, s15
	s_mul_i32 s14, s15, 0xa0
	s_sub_i32 s16, s42, s14
	s_sext_i32_i16 s14, s16
	s_bfe_u32 s14, s14, 0x4001b
	s_add_i32 s14, s16, s14
	s_sext_i32_i16 s17, s14
	s_and_b32 s14, s14, 0xfff0
	s_sub_i32 s14, s16, s14
	s_sext_i32_i16 s19, s14
	s_lshl_b32 s14, s17, 4
	s_and_b32 s14, s14, 0xffffff00
	v_mov_b32_e32 v148, v132
	v_mov_b32_e32 v18, v132
	s_cmpk_lt_i32 s16, 0x50
	ds_read_b64 v[0:1], v133
	s_cselect_b32 s16, s3, 0xc00
	v_lshlrev_b32_e32 v9, 4, v18
	v_and_b32_e32 v8, 32, v18
	v_lshrrev_b32_e32 v10, 1, v18
	v_bitop3_b32 v8, v9, v8, 48 bitop3:0x6c
	s_add_i32 s18, s14, s16
	s_lshl_b32 s15, s15, 12
	s_lshl_b32 s16, s19, 8
	v_bfe_u32 v19, v18, 2, 4
	v_and_b32_e32 v20, 32, v10
	v_lshrrev_b32_e32 v21, 1, v8
	v_ashrrev_i32_e32 v22, 3, v18
	s_add_i32 s16, s16, s15
	v_or_b32_e32 v12, v21, v20
	v_and_or_b32 v8, v22, s21, v19
	s_ashr_i32 s17, s16, 31
	v_and_b32_e32 v11, 0xfffffc00, v9
	v_lshl_or_b32 v128, v8, 10, v12
	v_add_u32_e32 v8, 0x2000, v9
	v_add_u32_e32 v10, 0x4000, v9
	v_add_u32_e32 v9, 0x6000, v9
	s_lshl_b64 s[44:45], s[16:17], 11
	s_ashr_i32 s19, s18, 31
	v_ashrrev_i32_e32 v23, 7, v8
	v_ashrrev_i32_e32 v24, 7, v10
	v_ashrrev_i32_e32 v25, 7, v9
	s_waitcnt lgkmcnt(0)
	v_lshl_add_u64 v[2:3], v[0:1], 0, s[44:45]
	s_lshl_b64 s[18:19], s[18:19], 11
	v_and_or_b32 v8, v23, s21, v19
	v_and_or_b32 v10, v24, s21, v19
	v_and_or_b32 v9, v25, s21, v19
	v_add_u32_e32 v149, 0, v11
	v_lshl_add_u64 v[4:5], v[2:3], 0, s[4:5]
	v_lshl_add_u64 v[0:1], v[0:1], 0, s[18:19]
	v_lshl_or_b32 v8, v8, 10, v12
	v_lshl_or_b32 v10, v10, 10, v12
	v_lshl_or_b32 v12, v9, 10, v12
	v_add_u32_e32 v9, 0x8000, v149
	v_lshlrev_b64 v[14:15], 1, v[128:129]
	v_readfirstlane_b32 s15, v149
	v_lshl_add_u64 v[6:7], v[0:1], 0, s[6:7]
	v_add_co_u32_e32 v16, vcc, v4, v14
	v_addc_co_u32_e32 v17, vcc, v5, v15, vcc
	s_mov_b32 m0, s15
	v_readfirstlane_b32 s15, v9
	v_mov_b32_e32 v9, v129
	v_add_u32_e32 v11, 0x2000, v149
	s_cmp_lg_u32 s101, 0
	s_cbranch_scc1 .Lnxh_1040_7
	global_load_lds_dwordx4 v[16:17], off

.Lnxn_1040:
	s_waitcnt lgkmcnt(0)
	s_waitcnt lgkmcnt(3)
	v_mfma_f32_16x16x32_bf16 v[108:111], v[178:181], v[162:165], v[108:111]
	v_mfma_f32_16x16x32_bf16 v[92:95], v[178:181], v[166:169], v[92:95]
	v_mfma_f32_16x16x32_bf16 v[76:79], v[178:181], v[170:173], v[76:79]
	v_mfma_f32_16x16x32_bf16 v[60:63], v[178:181], v[174:177], v[60:63]
	ds_read_b128 v[240:243], v197
	ds_read_b128 v[244:247], v198
	s_waitcnt lgkmcnt(4)
	v_mfma_f32_16x16x32_bf16 v[104:107], v[182:185], v[162:165], v[104:107]
	v_mfma_f32_16x16x32_bf16 v[88:91], v[182:185], v[166:169], v[88:91]
	v_mfma_f32_16x16x32_bf16 v[72:75], v[182:185], v[170:173], v[72:75]
	v_mfma_f32_16x16x32_bf16 v[56:59], v[182:185], v[174:177], v[56:59]
	ds_read_b128 v[248:251], v199
	ds_read_b128 v[252:255], v200
	s_waitcnt lgkmcnt(5)
	v_mfma_f32_16x16x32_bf16 v[100:103], v[186:189], v[162:165], v[100:103]
	v_mfma_f32_16x16x32_bf16 v[84:87], v[186:189], v[166:169], v[84:87]
	v_mfma_f32_16x16x32_bf16 v[68:71], v[186:189], v[170:173], v[68:71]
	v_mfma_f32_16x16x32_bf16 v[52:55], v[186:189], v[174:177], v[52:55]
	s_waitcnt lgkmcnt(4)
	v_mfma_f32_16x16x32_bf16 v[96:99], v[190:193], v[162:165], v[96:99]
	v_mfma_f32_16x16x32_bf16 v[80:83], v[190:193], v[166:169], v[80:83]
	v_mfma_f32_16x16x32_bf16 v[64:67], v[190:193], v[170:173], v[64:67]
	v_mfma_f32_16x16x32_bf16 v[48:51], v[190:193], v[174:177], v[48:51]
	ds_read_b128 v[162:165], v161 offset:1024
	ds_read_b128 v[166:169], v194 offset:1024
	ds_read_b128 v[170:173], v195 offset:1024
	ds_read_b128 v[174:177], v196 offset:1024
	s_waitcnt lgkmcnt(4)
	v_mfma_f32_16x16x32_bf16 v[44:47], v[178:181], v[240:243], v[44:47]
	v_mfma_f32_16x16x32_bf16 v[28:31], v[178:181], v[244:247], v[28:31]
	v_mfma_f32_16x16x32_bf16 v[12:15], v[178:181], v[248:251], v[12:15]
	v_mfma_f32_16x16x32_bf16 v[112:115], v[178:181], v[252:255], v[112:115]
	ds_read_b128 v[178:181], v128 offset:33792
	v_mfma_f32_16x16x32_bf16 v[40:43], v[182:185], v[240:243], v[40:43]
	v_mfma_f32_16x16x32_bf16 v[24:27], v[182:185], v[244:247], v[24:27]
	v_mfma_f32_16x16x32_bf16 v[8:11], v[182:185], v[248:251], v[8:11]
	v_mfma_f32_16x16x32_bf16 v[116:119], v[182:185], v[252:255], v[116:119]
	ds_read_b128 v[182:185], v128 offset:35840
	v_mfma_f32_16x16x32_bf16 v[36:39], v[186:189], v[240:243], v[36:39]
	v_mfma_f32_16x16x32_bf16 v[20:23], v[186:189], v[244:247], v[20:23]
	v_mfma_f32_16x16x32_bf16 v[4:7], v[186:189], v[248:251], v[4:7]
	v_mfma_f32_16x16x32_bf16 v[120:123], v[186:189], v[252:255], v[120:123]
	ds_read_b128 v[186:189], v128 offset:37888
	v_mfma_f32_16x16x32_bf16 v[32:35], v[190:193], v[240:243], v[32:35]
	v_mfma_f32_16x16x32_bf16 v[16:19], v[190:193], v[244:247], v[16:19]
	v_mfma_f32_16x16x32_bf16 v[0:3], v[190:193], v[248:251], v[0:3]
	v_mfma_f32_16x16x32_bf16 v[124:127], v[190:193], v[252:255], v[124:127]
	ds_read_b128 v[190:193], v128 offset:39936
	s_waitcnt lgkmcnt(3)
	v_mfma_f32_16x16x32_bf16 v[108:111], v[178:181], v[162:165], v[108:111]
	v_mfma_f32_16x16x32_bf16 v[92:95], v[178:181], v[166:169], v[92:95]
	v_mfma_f32_16x16x32_bf16 v[76:79], v[178:181], v[170:173], v[76:79]
	v_mfma_f32_16x16x32_bf16 v[60:63], v[178:181], v[174:177], v[60:63]
	ds_read_b128 v[240:243], v197 offset:1024
	ds_read_b128 v[244:247], v198 offset:1024
	s_waitcnt lgkmcnt(4)
	v_mfma_f32_16x16x32_bf16 v[104:107], v[182:185], v[162:165], v[104:107]
	v_mfma_f32_16x16x32_bf16 v[88:91], v[182:185], v[166:169], v[88:91]
	v_mfma_f32_16x16x32_bf16 v[72:75], v[182:185], v[170:173], v[72:75]
	v_mfma_f32_16x16x32_bf16 v[56:59], v[182:185], v[174:177], v[56:59]
	ds_read_b128 v[248:251], v199 offset:1024
	ds_read_b128 v[252:255], v200 offset:1024
	s_waitcnt lgkmcnt(5)
	v_mfma_f32_16x16x32_bf16 v[100:103], v[186:189], v[162:165], v[100:103]
	v_mfma_f32_16x16x32_bf16 v[84:87], v[186:189], v[166:169], v[84:87]
	v_mfma_f32_16x16x32_bf16 v[68:71], v[186:189], v[170:173], v[68:71]
	v_mfma_f32_16x16x32_bf16 v[52:55], v[186:189], v[174:177], v[52:55]
	s_waitcnt lgkmcnt(4)
	v_mfma_f32_16x16x32_bf16 v[96:99], v[190:193], v[162:165], v[96:99]
	v_mfma_f32_16x16x32_bf16 v[80:83], v[190:193], v[166:169], v[80:83]
	v_mfma_f32_16x16x32_bf16 v[64:67], v[190:193], v[170:173], v[64:67]
	v_mfma_f32_16x16x32_bf16 v[48:51], v[190:193], v[174:177], v[48:51]
	s_waitcnt lgkmcnt(0)
	v_mfma_f32_16x16x32_bf16 v[44:47], v[178:181], v[240:243], v[44:47]
	v_mfma_f32_16x16x32_bf16 v[28:31], v[178:181], v[244:247], v[28:31]
	v_mfma_f32_16x16x32_bf16 v[12:15], v[178:181], v[248:251], v[12:15]
	v_mfma_f32_16x16x32_bf16 v[112:115], v[178:181], v[252:255], v[112:115]
	v_mfma_f32_16x16x32_bf16 v[40:43], v[182:185], v[240:243], v[40:43]
	v_mfma_f32_16x16x32_bf16 v[24:27], v[182:185], v[244:247], v[24:27]
	v_mfma_f32_16x16x32_bf16 v[8:11], v[182:185], v[248:251], v[8:11]
	v_mfma_f32_16x16x32_bf16 v[116:119], v[182:185], v[252:255], v[116:119]
	v_mfma_f32_16x16x32_bf16 v[36:39], v[186:189], v[240:243], v[36:39]
	v_mfma_f32_16x16x32_bf16 v[20:23], v[186:189], v[244:247], v[20:23]
	v_mfma_f32_16x16x32_bf16 v[4:7], v[186:189], v[248:251], v[4:7]
	v_mfma_f32_16x16x32_bf16 v[120:123], v[186:189], v[252:255], v[120:123]
	v_mfma_f32_16x16x32_bf16 v[32:35], v[190:193], v[240:243], v[32:35]
	v_mfma_f32_16x16x32_bf16 v[16:19], v[190:193], v[244:247], v[16:19]
	v_mfma_f32_16x16x32_bf16 v[0:3], v[190:193], v[248:251], v[0:3]
	v_mfma_f32_16x16x32_bf16 v[124:127], v[190:193], v[252:255], v[124:127]
	v_mov_b32_e32 v128, s20
	s_waitcnt vmcnt(8)
	s_barrier
	ds_read_b64 v[240:241], v128
	v_ashrrev_i32_e32 v128, 1, v148
	v_and_b32_e32 v128, 0xffffff80, v128
	v_add_u32_e32 v128, s16, v128
	s_ashr_i32 s15, s14, 31
	s_waitcnt lgkmcnt(0)
	v_mad_i64_i32 v[240:241], s[16:17], v128, s26, v[240:241]
	v_and_b32_e32 v128, 0xc0, v148
	v_lshrrev_b32_e32 v243, 6, v148
	v_lshl_add_u64 v[240:241], s[14:15], 1, v[240:241]
	v_lshlrev_b32_e32 v128, 1, v128
	v_add_co_u32_e32 v240, vcc, v240, v128
	v_addc_co_u32_e32 v241, vcc, v241, v129, vcc
	v_mul_lo_u32 v128, v243, s27
	v_add_u32_e32 v243, s24, v128
	v_lshrrev_b32_e32 v128, 1, v148
	v_and_b32_e32 v244, 24, v128
	v_lshlrev_b32_e32 v128, 4, v148
	v_bfe_u32 v245, v148, 3, 3
	v_and_b32_e32 v242, 15, v148
	v_and_b32_e32 v128, 0x70, v128
	v_mul_u32_u24_e32 v246, 0x90, v245
	v_add_co_u32_e32 v240, vcc, v240, v128
	v_addc_co_u32_e32 v241, vcc, v241, v129, vcc
	v_add3_u32 v246, v243, v128, v246
	v_mul_u32_u24_e32 v128, 0x90, v242
	v_add3_u32 v242, v243, v244, v128
	v_cvt_pk_bf16_f32 v108, v108, v109
	v_cvt_pk_bf16_f32 v109, v110, v111
	v_cvt_pk_bf16_f32 v104, v104, v105
	v_cvt_pk_bf16_f32 v105, v106, v107
	v_cvt_pk_bf16_f32 v100, v100, v101
	v_cvt_pk_bf16_f32 v101, v102, v103
	v_cvt_pk_bf16_f32 v96, v96, v97
	v_cvt_pk_bf16_f32 v97, v98, v99
	v_cvt_pk_bf16_f32 v92, v92, v93
	v_cvt_pk_bf16_f32 v93, v94, v95
	v_cvt_pk_bf16_f32 v88, v88, v89
	v_cvt_pk_bf16_f32 v89, v90, v91
	v_cvt_pk_bf16_f32 v84, v84, v85
	v_cvt_pk_bf16_f32 v85, v86, v87
	v_cvt_pk_bf16_f32 v80, v80, v81
	v_cvt_pk_bf16_f32 v81, v82, v83
	v_cvt_pk_bf16_f32 v76, v76, v77
	v_cvt_pk_bf16_f32 v77, v78, v79
	v_cvt_pk_bf16_f32 v72, v72, v73
	v_cvt_pk_bf16_f32 v73, v74, v75
	v_cvt_pk_bf16_f32 v68, v68, v69
	v_cvt_pk_bf16_f32 v69, v70, v71
	v_cvt_pk_bf16_f32 v64, v64, v65
	v_cvt_pk_bf16_f32 v65, v66, v67
	v_cvt_pk_bf16_f32 v60, v60, v61
	v_cvt_pk_bf16_f32 v61, v62, v63
	v_cvt_pk_bf16_f32 v56, v56, v57
	v_cvt_pk_bf16_f32 v57, v58, v59
	v_cvt_pk_bf16_f32 v52, v52, v53
	v_cvt_pk_bf16_f32 v53, v54, v55
	v_cvt_pk_bf16_f32 v48, v48, v49
	v_cvt_pk_bf16_f32 v49, v50, v51
	ds_write_b64 v242, v[108:109]
	ds_write_b64 v242, v[104:105] offset:32
	ds_write_b64 v242, v[100:101] offset:64
	ds_write_b64 v242, v[96:97] offset:96
	ds_write_b64 v242, v[92:93] offset:2304
	ds_write_b64 v242, v[88:89] offset:2336
	ds_write_b64 v242, v[84:85] offset:2368
	ds_write_b64 v242, v[80:81] offset:2400
	ds_write_b64 v242, v[76:77] offset:4608
	ds_write_b64 v242, v[72:73] offset:4640
	ds_write_b64 v242, v[68:69] offset:4672
	ds_write_b64 v242, v[64:65] offset:4704
	ds_write_b64 v242, v[60:61] offset:6912
	ds_write_b64 v242, v[56:57] offset:6944
	ds_write_b64 v242, v[52:53] offset:6976
	ds_write_b64 v242, v[48:49] offset:7008
	ds_read_b128 v[48:51], v246
	v_mul_u32_u24_e32 v54, 0xa00, v245
	v_lshl_add_u64 v[52:53], v[240:241], 0, s[12:13]
	v_lshlrev_b32_e32 v128, 1, v54
	v_add_co_u32_e32 v54, vcc, v52, v128
	v_addc_co_u32_e32 v55, vcc, v53, v129, vcc
	s_waitcnt lgkmcnt(0)
	global_store_dwordx4 v[54:55], v[48:51], off nt
	ds_read_b128 v[48:51], v246 offset:1152
	v_add_co_u32_e32 v56, vcc, s22, v54
	v_cvt_pk_bf16_f32 v0, v0, v1
	s_nop 0
	v_addc_co_u32_e32 v57, vcc, 0, v55, vcc
	s_waitcnt lgkmcnt(0)
	global_store_dwordx4 v[56:57], v[48:51], off nt
	ds_read_b128 v[48:51], v246 offset:2304
	v_add_co_u32_e32 v56, vcc, s28, v54
	v_cvt_pk_bf16_f32 v1, v2, v3
	s_nop 0
	v_addc_co_u32_e32 v57, vcc, 0, v55, vcc
	s_waitcnt lgkmcnt(0)
	global_store_dwordx4 v[56:57], v[48:51], off nt
	ds_read_b128 v[48:51], v246 offset:3456
	v_add_co_u32_e32 v56, vcc, s29, v54
	v_cvt_pk_bf16_f32 v44, v44, v45
	s_nop 0
	v_addc_co_u32_e32 v57, vcc, 0, v55, vcc
	s_waitcnt lgkmcnt(0)
	global_store_dwordx4 v[56:57], v[48:51], off nt
	ds_read_b128 v[48:51], v246 offset:4608
	v_add_u32_e32 v56, 0x28000, v128
	v_mov_b32_e32 v57, v129
	v_add_co_u32_e32 v56, vcc, v52, v56
	v_addc_co_u32_e32 v57, vcc, v53, v57, vcc
	v_cvt_pk_bf16_f32 v45, v46, v47
	s_waitcnt lgkmcnt(0)
	global_store_dwordx4 v[56:57], v[48:51], off nt
	ds_read_b128 v[48:51], v246 offset:5760
	v_add_u32_e32 v56, 0x32000, v128
	v_mov_b32_e32 v57, v129
	v_add_co_u32_e32 v56, vcc, v52, v56
	v_addc_co_u32_e32 v57, vcc, v53, v57, vcc
	v_cvt_pk_bf16_f32 v40, v40, v41
	s_waitcnt lgkmcnt(0)
	global_store_dwordx4 v[56:57], v[48:51], off nt
	ds_read_b128 v[48:51], v246 offset:6912
	v_add_u32_e32 v56, 0x3c000, v128
	v_mov_b32_e32 v57, v129
	v_add_co_u32_e32 v56, vcc, v52, v56
	v_addc_co_u32_e32 v57, vcc, v53, v57, vcc
	v_add_u32_e32 v128, 0x46000, v128
	s_waitcnt lgkmcnt(0)
	global_store_dwordx4 v[56:57], v[48:51], off nt
	ds_read_b128 v[48:51], v246 offset:8064
	v_add_co_u32_e32 v52, vcc, v52, v128
	v_addc_co_u32_e32 v53, vcc, v53, v129, vcc
	v_cvt_pk_bf16_f32 v41, v42, v43
	v_cvt_pk_bf16_f32 v36, v36, v37
	v_cvt_pk_bf16_f32 v37, v38, v39
	s_waitcnt lgkmcnt(0)
	global_store_dwordx4 v[52:53], v[48:51], off nt
	ds_write_b64 v242, v[0:1] offset:4704
	v_cvt_pk_bf16_f32 v0, v112, v113
	v_cvt_pk_bf16_f32 v1, v114, v115
	ds_write_b64 v242, v[0:1] offset:6912
	v_cvt_pk_bf16_f32 v0, v116, v117
	v_cvt_pk_bf16_f32 v1, v118, v119
	ds_write_b64 v242, v[0:1] offset:6944
	v_cvt_pk_bf16_f32 v0, v120, v121
	v_cvt_pk_bf16_f32 v1, v122, v123
	v_cvt_pk_bf16_f32 v32, v32, v33
	v_cvt_pk_bf16_f32 v33, v34, v35
	v_cvt_pk_bf16_f32 v28, v28, v29
	v_cvt_pk_bf16_f32 v29, v30, v31
	v_cvt_pk_bf16_f32 v24, v24, v25
	v_cvt_pk_bf16_f32 v25, v26, v27
	v_cvt_pk_bf16_f32 v20, v20, v21
	v_cvt_pk_bf16_f32 v21, v22, v23
	v_cvt_pk_bf16_f32 v16, v16, v17
	v_cvt_pk_bf16_f32 v17, v18, v19
	v_cvt_pk_bf16_f32 v12, v12, v13
	v_cvt_pk_bf16_f32 v13, v14, v15
	v_cvt_pk_bf16_f32 v8, v8, v9
	v_cvt_pk_bf16_f32 v9, v10, v11
	v_cvt_pk_bf16_f32 v4, v4, v5
	v_cvt_pk_bf16_f32 v5, v6, v7
	ds_write_b64 v242, v[0:1] offset:6976
	v_cvt_pk_bf16_f32 v0, v124, v125
	v_cvt_pk_bf16_f32 v1, v126, v127
	ds_write_b64 v242, v[44:45]
	ds_write_b64 v242, v[40:41] offset:32
	ds_write_b64 v242, v[36:37] offset:64
	ds_write_b64 v242, v[32:33] offset:96
	ds_write_b64 v242, v[28:29] offset:2304
	ds_write_b64 v242, v[24:25] offset:2336
	ds_write_b64 v242, v[20:21] offset:2368
	ds_write_b64 v242, v[16:17] offset:2400
	ds_write_b64 v242, v[12:13] offset:4608
	ds_write_b64 v242, v[8:9] offset:4640
	ds_write_b64 v242, v[4:5] offset:4672
	ds_write_b64 v242, v[0:1] offset:7008
	ds_read_b128 v[0:3], v246
	v_add_co_u32_e32 v4, vcc, s30, v54
	s_add_i32 s42, s42, s40
	s_nop 0
	v_addc_co_u32_e32 v5, vcc, 0, v55, vcc
	s_waitcnt lgkmcnt(0)
	global_store_dwordx4 v[4:5], v[0:3], off nt
	ds_read_b128 v[0:3], v246 offset:1152
	v_add_co_u32_e32 v4, vcc, s31, v54
	s_cmpk_gt_i32 s42, 0x4ff
	s_nop 0
	v_addc_co_u32_e32 v5, vcc, 0, v55, vcc
	s_waitcnt lgkmcnt(0)
	global_store_dwordx4 v[4:5], v[0:3], off nt
	ds_read_b128 v[0:3], v246 offset:2304
	v_add_co_u32_e32 v4, vcc, s34, v54
	s_nop 1
	v_addc_co_u32_e32 v5, vcc, 0, v55, vcc
	s_waitcnt lgkmcnt(0)
	global_store_dwordx4 v[4:5], v[0:3], off nt
	ds_read_b128 v[0:3], v246 offset:3456
	v_add_co_u32_e32 v4, vcc, s35, v54
	s_nop 1
	v_addc_co_u32_e32 v5, vcc, 0, v55, vcc
	s_waitcnt lgkmcnt(0)
	global_store_dwordx4 v[4:5], v[0:3], off nt
	ds_read_b128 v[0:3], v246 offset:4608
	v_add_co_u32_e32 v4, vcc, s38, v54
	s_nop 1
	v_addc_co_u32_e32 v5, vcc, 0, v55, vcc
	s_waitcnt lgkmcnt(0)
	global_store_dwordx4 v[4:5], v[0:3], off nt
	ds_read_b128 v[0:3], v246 offset:5760
	v_add_co_u32_e32 v4, vcc, s39, v54
	s_nop 1
	v_addc_co_u32_e32 v5, vcc, 0, v55, vcc
	s_waitcnt lgkmcnt(0)
	global_store_dwordx4 v[4:5], v[0:3], off nt
	ds_read_b128 v[0:3], v246 offset:6912
	v_add_co_u32_e32 v4, vcc, 0x8c000, v54
	s_nop 1
	v_addc_co_u32_e32 v5, vcc, 0, v55, vcc
	s_waitcnt lgkmcnt(0)
	global_store_dwordx4 v[4:5], v[0:3], off nt
	ds_read_b128 v[0:3], v246 offset:8064
	v_add_co_u32_e32 v4, vcc, 0x96000, v54
	s_nop 1
	v_addc_co_u32_e32 v5, vcc, 0, v55, vcc
	s_waitcnt lgkmcnt(0)
	global_store_dwordx4 v[4:5], v[0:3], off nt
	s_cbranch_scc0 .LBB0_1039
	s_branch .Lfh_end_1040
.Lfh_1040:
	s_mul_hi_i32 s14, s42, 0x66666667
	s_lshr_b32 s15, s14, 31
	s_ashr_i32 s14, s14, 6
	s_add_i32 s15, s14, s15
	s_mul_i32 s14, s15, 0xa0
	s_sub_i32 s16, s42, s14
	s_sext_i32_i16 s14, s16
	s_bfe_u32 s14, s14, 0x4001b
	s_add_i32 s14, s16, s14
	s_sext_i32_i16 s17, s14
	s_and_b32 s14, s14, 0xfff0
	s_sub_i32 s14, s16, s14
	s_sext_i32_i16 s19, s14
	s_lshl_b32 s14, s17, 4
	s_and_b32 s14, s14, 0xffffff00
	s_cmpk_lt_i32 s16, 0x50
	s_cselect_b32 s16, s3, 0xc00
	s_add_i32 s18, s14, s16
	s_lshl_b32 s15, s15, 12
	s_lshl_b32 s16, s19, 8
	s_add_i32 s16, s16, s15
	s_ashr_i32 s17, s16, 31
	s_lshl_b64 s[44:45], s[16:17], 11
	s_ashr_i32 s19, s18, 31
	s_lshl_b64 s[18:19], s[18:19], 11
	s_mov_b64 s[18:19], 0
	s_mov_b32 s15, 0
	v_mov_b32_e32 v148, v132
	s_waitcnt vmcnt(16) lgkmcnt(0)
	s_barrier
	v_readfirstlane_b32 s100, v149
	s_and_b32 s17, s15, 0x10000
	s_xor_b32 s43, s17, 0x10000
	s_add_i32 s17, s17, 0
	v_add3_u32 v128, s17, v150, v151
	v_add3_u32 v161, s17, v150, v152
	v_add3_u32 v194, s17, v154, v153
	v_add3_u32 v195, s17, v154, v155
	v_add3_u32 v196, s17, v154, v156
	v_add3_u32 v197, s17, v154, v157
	v_add3_u32 v198, s17, v154, v158
	v_add3_u32 v199, s17, v154, v159
	v_add3_u32 v200, s17, v154, v160
	ds_read_b128 v[178:181], v128 offset:32768
	ds_read_b128 v[162:165], v161
	ds_read_b128 v[166:169], v194
	ds_read_b128 v[170:173], v195
	ds_read_b128 v[174:177], v196
	ds_read_b128 v[182:185], v128 offset:34816
	ds_read_b128 v[186:189], v128 offset:36864
	ds_read_b128 v[190:193], v128 offset:38912
	s_add_i32 s101, s100, s43
	v_readlane_b32 vcc_lo, v239, 0
	v_readlane_b32 vcc_hi, v239, 1
	s_add_u32 s98, s98, 0x80
	s_addc_u32 s99, s99, 0
	s_add_u32 vcc_lo, vcc_lo, 0x80
	s_addc_u32 vcc_hi, vcc_hi, 0
	s_mov_b32 m0, s101
	s_nop 0
	global_load_lds_dwordx4 v146, s[98:99]
	s_add_i32 m0, s101, 0x8000
	s_nop 0
	global_load_lds_dwordx4 v138, vcc
	s_add_i32 m0, s101, 0x2000
	s_nop 0
	global_load_lds_dwordx4 v144, s[98:99]
	s_add_i32 m0, s101, 0xa000
	s_nop 0
	global_load_lds_dwordx4 v136, vcc
	s_add_i32 m0, s101, 0x4000
	s_nop 0
	global_load_lds_dwordx4 v142, s[98:99]
	s_add_i32 m0, s101, 0xc000
	s_nop 0
	global_load_lds_dwordx4 v134, vcc
	s_add_i32 m0, s101, 0x6000
	s_nop 0
	global_load_lds_dwordx4 v140, s[98:99]
	s_add_i32 m0, s101, 0xe000
	s_nop 0
	global_load_lds_dwordx4 v130, vcc
	s_branch .LBB0_1040
